# attention fast trip: next-tile K fragment reads one gap earlier (gaps 2-5), step-closing wait+barrier moved up two P.V MFMA gaps
# speedup vs baseline: 1.0125x; 1.0036x over previous
.Lf3_0_486:
	s_waitcnt lgkmcnt(14)
	v_mfma_f32_32x32x16_bf16 v[18:33], v[138:141], v[178:181], v[18:33]
	v_exp_f32_e32 v98, v98
	v_exp_f32_e32 v99, v99
	v_exp_f32_e32 v100, v100
	v_exp_f32_e32 v101, v101
	ds_read_b128 v[62:65], v202 offset:16384
	ds_read_b128 v[178:181], v202 offset:18432
	s_waitcnt lgkmcnt(14)
	v_mfma_f32_32x32x16_bf16 v[2:17], v[138:141], v[174:177], v[2:17]
	v_exp_f32_e32 v102, v102
	v_exp_f32_e32 v103, v103
	v_exp_f32_e32 v104, v104
	v_exp_f32_e32 v105, v105
	ds_read_b128 v[174:177], v202 offset:16896
	ds_read_b128 v[170:173], v202 offset:18944
	s_waitcnt lgkmcnt(14)
	v_mfma_f32_32x32x16_bf16 v[18:33], v[130:133], v[66:69], v[18:33]
	v_exp_f32_e32 v106, v106
	v_exp_f32_e32 v107, v107
	v_exp_f32_e32 v108, v108
	v_exp_f32_e32 v109, v109
	ds_read_b128 v[166:169], v202 offset:20480
	ds_read_b128 v[162:165], v202 offset:20992
	s_waitcnt lgkmcnt(14)
	v_mfma_f32_32x32x16_bf16 v[2:17], v[130:133], v[70:73], v[2:17]
	v_exp_f32_e32 v110, v110
	v_exp_f32_e32 v111, v111
	v_exp_f32_e32 v112, v112
	v_exp_f32_e32 v113, v113
	ds_read_b128 v[158:161], v202 offset:22528
	ds_read_b128 v[154:157], v202 offset:23040
	s_waitcnt lgkmcnt(14)
	v_mfma_f32_32x32x16_bf16 v[18:33], v[122:125], v[74:77], v[18:33]
	v_exp_f32_e32 v82, v82
	v_exp_f32_e32 v83, v83
	v_exp_f32_e32 v84, v84
	v_exp_f32_e32 v85, v85
	s_waitcnt lgkmcnt(12)
	v_mfma_f32_32x32x16_bf16 v[2:17], v[122:125], v[50:53], v[2:17]
	v_exp_f32_e32 v86, v86
	v_exp_f32_e32 v87, v87
	v_exp_f32_e32 v88, v88
	v_exp_f32_e32 v89, v89
	s_waitcnt vmcnt(2) lgkmcnt(0)
	s_barrier
	s_waitcnt lgkmcnt(10)
	v_mfma_f32_32x32x16_bf16 v[18:33], v[114:117], v[54:57], v[18:33]
	v_exp_f32_e32 v90, v90
	v_exp_f32_e32 v91, v91
	v_exp_f32_e32 v92, v92
	v_exp_f32_e32 v93, v93
	s_waitcnt lgkmcnt(8)
	v_mfma_f32_32x32x16_bf16 v[2:17], v[114:117], v[58:61], v[2:17]
	v_exp_f32_e32 v94, v94
	v_exp_f32_e32 v95, v95
	v_exp_f32_e32 v96, v96
	v_exp_f32_e32 v97, v97

.Lf3_0_489:
	s_waitcnt lgkmcnt(14)
	v_mfma_f32_32x32x16_bf16 v[18:33], v[138:141], v[150:153], v[18:33]
	v_exp_f32_e32 v66, v66
	v_exp_f32_e32 v67, v67
	v_exp_f32_e32 v68, v68
	v_exp_f32_e32 v69, v69
	ds_read_b128 v[174:177], v202 offset:0
	ds_read_b128 v[170:173], v202 offset:512
	s_waitcnt lgkmcnt(14)
	v_mfma_f32_32x32x16_bf16 v[2:17], v[138:141], v[146:149], v[2:17]
	v_exp_f32_e32 v70, v70
	v_exp_f32_e32 v71, v71
	v_exp_f32_e32 v72, v72
	v_exp_f32_e32 v73, v73
	ds_read_b128 v[166:169], v202 offset:2048
	ds_read_b128 v[162:165], v202 offset:2560
	s_waitcnt lgkmcnt(14)
	v_mfma_f32_32x32x16_bf16 v[18:33], v[130:133], v[98:101], v[18:33]
	v_exp_f32_e32 v74, v74
	v_exp_f32_e32 v75, v75
	v_exp_f32_e32 v76, v76
	v_exp_f32_e32 v77, v77
	ds_read_b128 v[158:161], v202 offset:4096
	ds_read_b128 v[154:157], v202 offset:4608
	s_waitcnt lgkmcnt(14)
	v_mfma_f32_32x32x16_bf16 v[2:17], v[130:133], v[102:105], v[2:17]
	v_exp_f32_e32 v78, v78
	v_exp_f32_e32 v79, v79
	v_exp_f32_e32 v80, v80
	v_exp_f32_e32 v81, v81
	ds_read_b128 v[150:153], v202 offset:6144
	ds_read_b128 v[146:149], v202 offset:6656
	s_waitcnt lgkmcnt(14)
	v_mfma_f32_32x32x16_bf16 v[18:33], v[122:125], v[106:109], v[18:33]
	v_exp_f32_e32 v50, v50
	v_exp_f32_e32 v51, v51
	v_exp_f32_e32 v52, v52
	v_exp_f32_e32 v53, v53
	s_waitcnt lgkmcnt(12)
	v_mfma_f32_32x32x16_bf16 v[2:17], v[122:125], v[82:85], v[2:17]
	v_exp_f32_e32 v54, v54
	v_exp_f32_e32 v55, v55
	v_exp_f32_e32 v56, v56
	v_exp_f32_e32 v57, v57
	s_waitcnt vmcnt(2) lgkmcnt(0)
	s_barrier
	s_waitcnt lgkmcnt(10)
	v_mfma_f32_32x32x16_bf16 v[18:33], v[114:117], v[86:89], v[18:33]
	v_exp_f32_e32 v58, v58
	v_exp_f32_e32 v59, v59
	v_exp_f32_e32 v60, v60
	v_exp_f32_e32 v61, v61
	s_waitcnt lgkmcnt(8)
	v_mfma_f32_32x32x16_bf16 v[2:17], v[114:117], v[90:93], v[2:17]
	v_exp_f32_e32 v62, v62
	v_exp_f32_e32 v63, v63
	v_exp_f32_e32 v64, v64
	v_exp_f32_e32 v65, v65

.Lf3_1_486:
	s_waitcnt lgkmcnt(14)
	v_mfma_f32_32x32x16_bf16 v[18:33], v[138:141], v[178:181], v[18:33]
	v_exp_f32_e32 v98, v98
	v_exp_f32_e32 v99, v99
	v_exp_f32_e32 v100, v100
	v_exp_f32_e32 v101, v101
	ds_read_b128 v[62:65], v202 offset:8192
	ds_read_b128 v[178:181], v202 offset:10240
	s_waitcnt lgkmcnt(14)
	v_mfma_f32_32x32x16_bf16 v[2:17], v[138:141], v[174:177], v[2:17]
	v_exp_f32_e32 v102, v102
	v_exp_f32_e32 v103, v103
	v_exp_f32_e32 v104, v104
	v_exp_f32_e32 v105, v105
	ds_read_b128 v[174:177], v202 offset:8704
	ds_read_b128 v[170:173], v202 offset:10752
	s_waitcnt lgkmcnt(14)
	v_mfma_f32_32x32x16_bf16 v[18:33], v[130:133], v[66:69], v[18:33]
	v_exp_f32_e32 v106, v106
	v_exp_f32_e32 v107, v107
	v_exp_f32_e32 v108, v108
	v_exp_f32_e32 v109, v109
	ds_read_b128 v[166:169], v202 offset:12288
	ds_read_b128 v[162:165], v202 offset:12800
	s_waitcnt lgkmcnt(14)
	v_mfma_f32_32x32x16_bf16 v[2:17], v[130:133], v[70:73], v[2:17]
	v_exp_f32_e32 v110, v110
	v_exp_f32_e32 v111, v111
	v_exp_f32_e32 v112, v112
	v_exp_f32_e32 v113, v113
	ds_read_b128 v[158:161], v202 offset:14336
	ds_read_b128 v[154:157], v202 offset:14848
	s_waitcnt lgkmcnt(14)
	v_mfma_f32_32x32x16_bf16 v[18:33], v[122:125], v[74:77], v[18:33]
	v_exp_f32_e32 v82, v82
	v_exp_f32_e32 v83, v83
	v_exp_f32_e32 v84, v84
	v_exp_f32_e32 v85, v85
	s_waitcnt lgkmcnt(12)
	v_mfma_f32_32x32x16_bf16 v[2:17], v[122:125], v[50:53], v[2:17]
	v_exp_f32_e32 v86, v86
	v_exp_f32_e32 v87, v87
	v_exp_f32_e32 v88, v88
	v_exp_f32_e32 v89, v89
	s_waitcnt vmcnt(2) lgkmcnt(0)
	s_barrier
	s_waitcnt lgkmcnt(10)
	v_mfma_f32_32x32x16_bf16 v[18:33], v[114:117], v[54:57], v[18:33]
	v_exp_f32_e32 v90, v90
	v_exp_f32_e32 v91, v91
	v_exp_f32_e32 v92, v92
	v_exp_f32_e32 v93, v93
	s_waitcnt lgkmcnt(8)
	v_mfma_f32_32x32x16_bf16 v[2:17], v[114:117], v[58:61], v[2:17]
	v_exp_f32_e32 v94, v94
	v_exp_f32_e32 v95, v95
	v_exp_f32_e32 v96, v96
	v_exp_f32_e32 v97, v97

.Lf3_1_489:
	s_waitcnt lgkmcnt(14)
	v_mfma_f32_32x32x16_bf16 v[18:33], v[138:141], v[150:153], v[18:33]
	v_exp_f32_e32 v66, v66
	v_exp_f32_e32 v67, v67
	v_exp_f32_e32 v68, v68
	v_exp_f32_e32 v69, v69
	ds_read_b128 v[174:177], v202 offset:16384
	ds_read_b128 v[170:173], v202 offset:16896
	s_waitcnt lgkmcnt(14)
	v_mfma_f32_32x32x16_bf16 v[2:17], v[138:141], v[146:149], v[2:17]
	v_exp_f32_e32 v70, v70
	v_exp_f32_e32 v71, v71
	v_exp_f32_e32 v72, v72
	v_exp_f32_e32 v73, v73
	ds_read_b128 v[166:169], v202 offset:18432
	ds_read_b128 v[162:165], v202 offset:18944
	s_waitcnt lgkmcnt(14)
	v_mfma_f32_32x32x16_bf16 v[18:33], v[130:133], v[98:101], v[18:33]
	v_exp_f32_e32 v74, v74
	v_exp_f32_e32 v75, v75
	v_exp_f32_e32 v76, v76
	v_exp_f32_e32 v77, v77
	ds_read_b128 v[158:161], v202 offset:20480
	ds_read_b128 v[154:157], v202 offset:20992
	s_waitcnt lgkmcnt(14)
	v_mfma_f32_32x32x16_bf16 v[2:17], v[130:133], v[102:105], v[2:17]
	v_exp_f32_e32 v78, v78
	v_exp_f32_e32 v79, v79
	v_exp_f32_e32 v80, v80
	v_exp_f32_e32 v81, v81
	ds_read_b128 v[150:153], v202 offset:22528
	ds_read_b128 v[146:149], v202 offset:23040
	s_waitcnt lgkmcnt(14)
	v_mfma_f32_32x32x16_bf16 v[18:33], v[122:125], v[106:109], v[18:33]
	v_exp_f32_e32 v50, v50
	v_exp_f32_e32 v51, v51
	v_exp_f32_e32 v52, v52
	v_exp_f32_e32 v53, v53
	s_waitcnt lgkmcnt(12)
	v_mfma_f32_32x32x16_bf16 v[2:17], v[122:125], v[82:85], v[2:17]
	v_exp_f32_e32 v54, v54
	v_exp_f32_e32 v55, v55
	v_exp_f32_e32 v56, v56
	v_exp_f32_e32 v57, v57
	s_waitcnt vmcnt(2) lgkmcnt(0)
	s_barrier
	s_waitcnt lgkmcnt(10)
	v_mfma_f32_32x32x16_bf16 v[18:33], v[114:117], v[86:89], v[18:33]
	v_exp_f32_e32 v58, v58
	v_exp_f32_e32 v59, v59
	v_exp_f32_e32 v60, v60
	v_exp_f32_e32 v61, v61
	s_waitcnt lgkmcnt(8)
	v_mfma_f32_32x32x16_bf16 v[2:17], v[114:117], v[90:93], v[2:17]
	v_exp_f32_e32 v62, v62
	v_exp_f32_e32 v63, v63
	v_exp_f32_e32 v64, v64
	v_exp_f32_e32 v65, v65

.Lf3_2_486:
	s_waitcnt lgkmcnt(14)
	v_mfma_f32_32x32x16_bf16 v[18:33], v[138:141], v[178:181], v[18:33]
	v_exp_f32_e32 v98, v98
	v_exp_f32_e32 v99, v99
	v_exp_f32_e32 v100, v100
	v_exp_f32_e32 v101, v101
	ds_read_b128 v[62:65], v202 offset:0
	ds_read_b128 v[178:181], v202 offset:2048
	s_waitcnt lgkmcnt(14)
	v_mfma_f32_32x32x16_bf16 v[2:17], v[138:141], v[174:177], v[2:17]
	v_exp_f32_e32 v102, v102
	v_exp_f32_e32 v103, v103
	v_exp_f32_e32 v104, v104
	v_exp_f32_e32 v105, v105
	ds_read_b128 v[174:177], v202 offset:512
	ds_read_b128 v[170:173], v202 offset:2560
	s_waitcnt lgkmcnt(14)
	v_mfma_f32_32x32x16_bf16 v[18:33], v[130:133], v[66:69], v[18:33]
	v_exp_f32_e32 v106, v106
	v_exp_f32_e32 v107, v107
	v_exp_f32_e32 v108, v108
	v_exp_f32_e32 v109, v109
	ds_read_b128 v[166:169], v202 offset:4096
	ds_read_b128 v[162:165], v202 offset:4608
	s_waitcnt lgkmcnt(14)
	v_mfma_f32_32x32x16_bf16 v[2:17], v[130:133], v[70:73], v[2:17]
	v_exp_f32_e32 v110, v110
	v_exp_f32_e32 v111, v111
	v_exp_f32_e32 v112, v112
	v_exp_f32_e32 v113, v113
	ds_read_b128 v[158:161], v202 offset:6144
	ds_read_b128 v[154:157], v202 offset:6656
	s_waitcnt lgkmcnt(14)
	v_mfma_f32_32x32x16_bf16 v[18:33], v[122:125], v[74:77], v[18:33]
	v_exp_f32_e32 v82, v82
	v_exp_f32_e32 v83, v83
	v_exp_f32_e32 v84, v84
	v_exp_f32_e32 v85, v85
	s_waitcnt lgkmcnt(12)
	v_mfma_f32_32x32x16_bf16 v[2:17], v[122:125], v[50:53], v[2:17]
	v_exp_f32_e32 v86, v86
	v_exp_f32_e32 v87, v87
	v_exp_f32_e32 v88, v88
	v_exp_f32_e32 v89, v89
	s_waitcnt vmcnt(2) lgkmcnt(0)
	s_barrier
	s_waitcnt lgkmcnt(10)
	v_mfma_f32_32x32x16_bf16 v[18:33], v[114:117], v[54:57], v[18:33]
	v_exp_f32_e32 v90, v90
	v_exp_f32_e32 v91, v91
	v_exp_f32_e32 v92, v92
	v_exp_f32_e32 v93, v93
	s_waitcnt lgkmcnt(8)
	v_mfma_f32_32x32x16_bf16 v[2:17], v[114:117], v[58:61], v[2:17]
	v_exp_f32_e32 v94, v94
	v_exp_f32_e32 v95, v95
	v_exp_f32_e32 v96, v96
	v_exp_f32_e32 v97, v97

.Lf3_2_489:
	s_waitcnt lgkmcnt(14)
	v_mfma_f32_32x32x16_bf16 v[18:33], v[138:141], v[150:153], v[18:33]
	v_exp_f32_e32 v66, v66
	v_exp_f32_e32 v67, v67
	v_exp_f32_e32 v68, v68
	v_exp_f32_e32 v69, v69
	ds_read_b128 v[174:177], v202 offset:8192
	ds_read_b128 v[170:173], v202 offset:8704
	s_waitcnt lgkmcnt(14)
	v_mfma_f32_32x32x16_bf16 v[2:17], v[138:141], v[146:149], v[2:17]
	v_exp_f32_e32 v70, v70
	v_exp_f32_e32 v71, v71
	v_exp_f32_e32 v72, v72
	v_exp_f32_e32 v73, v73
	ds_read_b128 v[166:169], v202 offset:10240
	ds_read_b128 v[162:165], v202 offset:10752
	s_waitcnt lgkmcnt(14)
	v_mfma_f32_32x32x16_bf16 v[18:33], v[130:133], v[98:101], v[18:33]
	v_exp_f32_e32 v74, v74
	v_exp_f32_e32 v75, v75
	v_exp_f32_e32 v76, v76
	v_exp_f32_e32 v77, v77
	ds_read_b128 v[158:161], v202 offset:12288
	ds_read_b128 v[154:157], v202 offset:12800
	s_waitcnt lgkmcnt(14)
	v_mfma_f32_32x32x16_bf16 v[2:17], v[130:133], v[102:105], v[2:17]
	v_exp_f32_e32 v78, v78
	v_exp_f32_e32 v79, v79
	v_exp_f32_e32 v80, v80
	v_exp_f32_e32 v81, v81
	ds_read_b128 v[150:153], v202 offset:14336
	ds_read_b128 v[146:149], v202 offset:14848
	s_waitcnt lgkmcnt(14)
	v_mfma_f32_32x32x16_bf16 v[18:33], v[122:125], v[106:109], v[18:33]
	v_exp_f32_e32 v50, v50
	v_exp_f32_e32 v51, v51
	v_exp_f32_e32 v52, v52
	v_exp_f32_e32 v53, v53
	s_waitcnt lgkmcnt(12)
	v_mfma_f32_32x32x16_bf16 v[2:17], v[122:125], v[82:85], v[2:17]
	v_exp_f32_e32 v54, v54
	v_exp_f32_e32 v55, v55
	v_exp_f32_e32 v56, v56
	v_exp_f32_e32 v57, v57
	s_waitcnt vmcnt(2) lgkmcnt(0)
	s_barrier
	s_waitcnt lgkmcnt(10)
	v_mfma_f32_32x32x16_bf16 v[18:33], v[114:117], v[86:89], v[18:33]
	v_exp_f32_e32 v58, v58
	v_exp_f32_e32 v59, v59
	v_exp_f32_e32 v60, v60
	v_exp_f32_e32 v61, v61
	s_waitcnt lgkmcnt(8)
	v_mfma_f32_32x32x16_bf16 v[2:17], v[114:117], v[90:93], v[2:17]
	v_exp_f32_e32 v62, v62
	v_exp_f32_e32 v63, v63
	v_exp_f32_e32 v64, v64
	v_exp_f32_e32 v65, v65
